# norm phases: sample rows spread over all work-groups (row = gw>>2 on waves with gw%4==0) instead of 8 per WG on 64 WGs
# speedup vs baseline: 1.0078x; 1.0063x over previous
.LBB0_254:
	s_or_b64 exec, exec, s[26:27]
	s_movk_i32 s0, 0x200
	v_and_b32_e32 v16, 3, v64
	v_lshrrev_b32_e32 v64, 2, v64
	v_cmp_eq_u32_e32 vcc, 0, v16
	s_and_saveexec_b64 s[22:23], vcc
	s_cbranch_execz .LBB0_257
	v_mbcnt_lo_u32_b32 v16, -1, 0
	v_mbcnt_hi_u32_b32 v16, -1, v16
	v_and_b32_e32 v17, 64, v16
	v_add_u32_e32 v17, 64, v17
	v_xor_b32_e32 v18, 1, v16
	v_cmp_lt_i32_e32 vcc, v18, v17
	v_ashrrev_i32_e32 v65, 31, v64
	v_readlane_b32 s36, v254, 11
	v_cndmask_b32_e32 v18, v16, v18, vcc
	v_lshlrev_b32_e32 v30, 2, v18
	v_xor_b32_e32 v18, 2, v16
	v_cmp_lt_i32_e32 vcc, v18, v17
	v_mov_b32_e32 v75, 0
	v_readlane_b32 s38, v254, 13
	v_cndmask_b32_e32 v18, v16, v18, vcc
	v_lshlrev_b32_e32 v31, 2, v18
	v_xor_b32_e32 v18, 4, v16
	v_cmp_lt_i32_e32 vcc, v18, v17
	v_readlane_b32 s39, v254, 14
	v_readlane_b32 s48, v254, 23
	v_cndmask_b32_e32 v18, v16, v18, vcc
	v_lshlrev_b32_e32 v32, 2, v18
	v_xor_b32_e32 v18, 8, v16
	v_cmp_lt_i32_e32 vcc, v18, v17
	v_readlane_b32 s49, v254, 24
	s_ashr_i32 s19, s18, 31
	v_cndmask_b32_e32 v18, v16, v18, vcc
	v_lshlrev_b32_e32 v33, 2, v18
	v_xor_b32_e32 v18, 16, v16
	v_cmp_lt_i32_e32 vcc, v18, v17
	v_lshl_add_u64 v[24:25], s[24:25], 0, v[74:75]
	s_lshl_b64 s[26:27], s[18:19], 12
	v_cndmask_b32_e32 v18, v16, v18, vcc
	v_lshlrev_b32_e32 v34, 2, v18
	v_xor_b32_e32 v18, 32, v16
	v_cmp_lt_i32_e32 vcc, v18, v17
	s_mov_b64 s[30:31], 0
	s_mov_b32 s3, 0x9000
	v_cndmask_b32_e32 v16, v16, v18, vcc
	v_lshlrev_b32_e32 v35, 2, v16
	v_lshlrev_b64 v[16:17], 12, v[64:65]
	v_lshl_or_b32 v16, v144, 4, v16
	v_lshl_add_u64 v[26:27], s[38:39], 0, v[16:17]
	v_mov_b64_e32 v[28:29], s[96:97]
	v_mov_b32_e32 v36, 0x358637bd
	s_mov_b32 s6, 0xf800000
	v_mov_b32_e32 v37, 0x260
	s_mov_b64 s[48:49], 0x1000
	v_mov_b32_e32 v67, v75
	v_mov_b32_e32 v69, v75
	v_mov_b32_e32 v71, v75
	v_mov_b32_e32 v73, v75
	s_movk_i32 s7, 0x1ff
	v_readlane_b32 s37, v254, 12
	v_readlane_b32 s40, v254, 15
	v_readlane_b32 s41, v254, 16
	v_readlane_b32 s42, v254, 17
	v_readlane_b32 s43, v254, 18
	v_readlane_b32 s44, v254, 19
	v_readlane_b32 s45, v254, 20
	v_readlane_b32 s46, v254, 21
	v_readlane_b32 s47, v254, 22
	v_readlane_b32 s50, v254, 25
	v_readlane_b32 s51, v254, 26

.LBB0_499:
	s_or_b64 exec, exec, s[36:37]
	s_movk_i32 s0, 0x200
	v_and_b32_e32 v16, 3, v50
	v_lshrrev_b32_e32 v50, 2, v50
	v_cmp_eq_u32_e32 vcc, 0, v16
	s_and_saveexec_b64 s[36:37], vcc
	s_cbranch_execz .LBB0_502
	v_mbcnt_lo_u32_b32 v16, -1, 0
	v_mbcnt_hi_u32_b32 v16, -1, v16
	v_and_b32_e32 v18, 64, v16
	v_add_u32_e32 v18, 64, v18
	v_xor_b32_e32 v19, 1, v16
	v_cmp_lt_i32_e32 vcc, v19, v18
	v_ashrrev_i32_e32 v51, 31, v50
	v_lshlrev_b64 v[24:25], 12, v[50:51]
	v_cndmask_b32_e32 v19, v16, v19, vcc
	v_lshlrev_b32_e32 v40, 2, v19
	v_xor_b32_e32 v19, 2, v16
	v_cmp_lt_i32_e32 vcc, v19, v18
	s_mov_b64 s[12:13], s[84:85]
	v_lshl_add_u64 v[20:21], s[94:95], 0, v[24:25]
	v_cndmask_b32_e32 v19, v16, v19, vcc
	v_lshlrev_b32_e32 v41, 2, v19
	v_xor_b32_e32 v19, 4, v16
	v_cmp_lt_i32_e32 vcc, v19, v18
	s_mov_b64 s[14:15], s[86:87]
	v_readlane_b32 s80, v254, 11
	v_cndmask_b32_e32 v19, v16, v19, vcc
	v_lshlrev_b32_e32 v42, 2, v19
	v_xor_b32_e32 v19, 8, v16
	v_cmp_lt_i32_e32 vcc, v19, v18
	v_readlane_b32 s8, v254, 0
	v_readlane_b32 s84, v254, 15
	v_cndmask_b32_e32 v19, v16, v19, vcc
	v_lshlrev_b32_e32 v43, 2, v19
	v_xor_b32_e32 v19, 16, v16
	v_cmp_lt_i32_e32 vcc, v19, v18
	v_readlane_b32 s85, v254, 16
	v_readlane_b32 s86, v254, 17
	v_cndmask_b32_e32 v19, v16, v19, vcc
	v_lshlrev_b32_e32 v44, 2, v19
	v_xor_b32_e32 v19, 32, v16
	v_cmp_lt_i32_e32 vcc, v19, v18
	v_readlane_b32 s87, v254, 18
	v_readlane_b32 s90, v254, 21
	v_cndmask_b32_e32 v16, v16, v19, vcc
	v_readlane_b32 s91, v254, 22
	v_readlane_b32 s94, v254, 25
	v_readlane_b32 s95, v254, 26
	v_or_b32_e32 v28, 0x100, v86
	v_mov_b32_e32 v17, 0
	v_or_b32_e32 v30, 0x200, v86
	v_or_b32_e32 v32, 0x300, v86
	v_lshlrev_b32_e32 v45, 2, v16
	v_lshlrev_b32_e32 v16, 1, v86
	s_ashr_i32 s31, s30, 31
	v_readlane_b32 s9, v254, 1
	v_readlane_b32 s10, v254, 2
	v_readlane_b32 s11, v254, 3
	v_readlane_b32 s82, v254, 13
	v_readlane_b32 s83, v254, 14
	v_readlane_b32 s90, v254, 61
	s_mov_b64 s[86:87], s[14:15]
	v_readlane_b32 s94, v254, 59
	v_lshl_add_u64 v[18:19], s[24:25], 0, v[16:17]
	v_mov_b32_e32 v49, v17
	s_lshl_b64 s[48:49], s[30:31], 12
	v_lshl_add_u64 v[22:23], s[10:11], 0, v[24:25]
	v_readlane_b32 s91, v254, 62
	s_mov_b64 s[84:85], s[12:13]
	v_readlane_b32 s95, v254, 60
	v_lshl_add_u64 v[24:25], s[82:83], 0, v[24:25]
	s_mov_b64 s[38:39], 0
	s_mov_b32 s3, 0xe800000
	s_mov_b32 s6, 0xea00000
	s_mov_b32 s7, 0xec00000
	s_mov_b32 s8, 0xee00000
	s_mov_b32 s9, 0xf000000
	s_mov_b32 s10, 0xf200000
	s_mov_b32 s11, 0xf400000
	s_mov_b32 s12, 0xf600000
	s_mov_b32 s13, 0xf800000
	s_mov_b32 s14, 0xfa00000
	s_mov_b32 s15, 0x9000
	v_mov_b64_e32 v[26:27], s[96:97]
	s_brev_b32 s16, 32
	v_mov_b32_e32 v46, 0x358637bd
	v_mov_b32_e32 v47, 0x260
	s_mov_b64 s[50:51], 0x4000
	s_mov_b64 s[52:53], 0x3000
	v_lshlrev_b32_e32 v16, 2, v86
	v_lshlrev_b32_e32 v28, 2, v28
	v_mov_b32_e32 v29, v17
	v_lshlrev_b32_e32 v30, 2, v30
	v_mov_b32_e32 v31, v17
	v_lshlrev_b32_e32 v32, 2, v32
	v_mov_b32_e32 v33, v17
	s_movk_i32 s17, 0x1ff
	v_readlane_b32 s81, v254, 12
	v_readlane_b32 s88, v254, 19
	v_readlane_b32 s89, v254, 20
	v_readlane_b32 s92, v254, 23
	v_readlane_b32 s93, v254, 24

.LBB0_1149:
	s_or_b64 exec, exec, s[10:11]
	s_movk_i32 s0, 0x200
	v_and_b32_e32 v16, 3, v50
	v_lshrrev_b32_e32 v50, 2, v50
	v_cmp_eq_u32_e32 vcc, 0, v16
	s_and_saveexec_b64 s[10:11], vcc
	s_cbranch_execz .LBB0_1152
	s_waitcnt vmcnt(0)
	v_mbcnt_lo_u32_b32 v16, -1, 0
	v_mbcnt_hi_u32_b32 v16, -1, v16
	v_and_b32_e32 v18, 64, v16
	v_add_u32_e32 v18, 64, v18
	v_xor_b32_e32 v19, 1, v16
	v_cmp_lt_i32_e32 vcc, v19, v18
	v_ashrrev_i32_e32 v51, 31, v50
	v_readlane_b32 s12, v254, 0
	v_cndmask_b32_e32 v19, v16, v19, vcc
	v_lshlrev_b32_e32 v36, 2, v19
	v_xor_b32_e32 v19, 2, v16
	v_cmp_lt_i32_e32 vcc, v19, v18
	v_or_b32_e32 v26, 0x100, v86
	v_mov_b32_e32 v17, 0
	v_cndmask_b32_e32 v19, v16, v19, vcc
	v_lshlrev_b32_e32 v37, 2, v19
	v_xor_b32_e32 v19, 4, v16
	v_cmp_lt_i32_e32 vcc, v19, v18
	v_or_b32_e32 v28, 0x200, v86
	v_or_b32_e32 v30, 0x300, v86
	v_cndmask_b32_e32 v19, v16, v19, vcc
	v_lshlrev_b32_e32 v38, 2, v19
	v_xor_b32_e32 v19, 8, v16
	v_cmp_lt_i32_e32 vcc, v19, v18
	v_lshlrev_b64 v[22:23], 12, v[50:51]
	v_readlane_b32 s13, v254, 1
	v_cndmask_b32_e32 v19, v16, v19, vcc
	v_lshlrev_b32_e32 v39, 2, v19
	v_xor_b32_e32 v19, 16, v16
	v_cmp_lt_i32_e32 vcc, v19, v18
	v_readlane_b32 s14, v254, 2
	v_readlane_b32 s15, v254, 3
	v_cndmask_b32_e32 v19, v16, v19, vcc
	v_lshlrev_b32_e32 v40, 2, v19
	v_xor_b32_e32 v19, 32, v16
	v_cmp_lt_i32_e32 vcc, v19, v18
	s_ashr_i32 s9, s8, 31
	v_mov_b32_e32 v49, v17
	v_cndmask_b32_e32 v16, v16, v19, vcc
	v_lshlrev_b32_e32 v41, 2, v16
	v_lshlrev_b32_e32 v16, 1, v86
	v_lshl_add_u64 v[18:19], s[24:25], 0, v[16:17]
	v_lshl_add_u64 v[20:21], s[14:15], 0, v[22:23]
	s_lshl_b64 s[12:13], s[8:9], 12
	v_lshl_add_u64 v[22:23], s[94:95], 0, v[22:23]
	s_mov_b64 s[14:15], 0
	s_mov_b32 s3, 0xe800000
	s_mov_b32 s6, 0xea00000
	s_mov_b32 s7, 0xec00000
	s_mov_b32 s9, 0xee00000
	s_mov_b32 s28, 0xf000000
	s_mov_b32 s29, 0xf200000
	s_mov_b32 s30, 0xf400000
	s_mov_b32 s31, 0x9000
	v_mov_b64_e32 v[24:25], s[96:97]
	v_mov_b32_e32 v42, 0x358637bd
	s_mov_b32 s36, 0xf800000
	v_mov_b32_e32 v43, 0x260
	s_mov_b64 s[16:17], 0x7000
	s_mov_b64 s[20:21], 0x6000
	v_lshlrev_b32_e32 v16, 2, v86
	v_lshlrev_b32_e32 v26, 2, v26
	v_mov_b32_e32 v27, v17
	v_lshlrev_b32_e32 v28, 2, v28
	v_mov_b32_e32 v29, v17
	v_lshlrev_b32_e32 v30, 2, v30
	v_mov_b32_e32 v31, v17
	s_movk_i32 s37, 0x1ff

.LBB0_1394:
	s_or_b64 exec, exec, s[4:5]
	s_movk_i32 s0, 0x200
	v_and_b32_e32 v16, 3, v50
	v_lshrrev_b32_e32 v50, 2, v50
	v_cmp_eq_u32_e32 vcc, 0, v16
	s_and_saveexec_b64 s[0:1], vcc
	s_cbranch_execz .LBB0_1397
	s_waitcnt vmcnt(0)
	v_mbcnt_hi_u32_b32 v16, -1, v49
	v_and_b32_e32 v17, 64, v16
	v_add_u32_e32 v17, 64, v17
	v_xor_b32_e32 v18, 1, v16
	v_cmp_lt_i32_e32 vcc, v18, v17
	v_readlane_b32 s8, v254, 0
	s_ashr_i32 s3, s2, 31
	v_cndmask_b32_e32 v18, v16, v18, vcc
	v_lshlrev_b32_e32 v24, 2, v18
	v_xor_b32_e32 v18, 2, v16
	v_cmp_lt_i32_e32 vcc, v18, v17
	v_readlane_b32 s9, v254, 1
	v_readlane_b32 s10, v254, 2
	v_cndmask_b32_e32 v18, v16, v18, vcc
	v_lshlrev_b32_e32 v25, 2, v18
	v_xor_b32_e32 v18, 4, v16
	v_cmp_lt_i32_e32 vcc, v18, v17
	v_readlane_b32 s11, v254, 3
	v_mov_b32_e32 v49, 0
	v_cndmask_b32_e32 v18, v16, v18, vcc
	v_lshlrev_b32_e32 v26, 2, v18
	v_xor_b32_e32 v18, 8, v16
	v_cmp_lt_i32_e32 vcc, v18, v17
	s_lshl_b64 s[4:5], s[2:3], 12
	s_mov_b64 s[6:7], 0
	v_cndmask_b32_e32 v18, v16, v18, vcc
	v_lshlrev_b32_e32 v27, 2, v18
	v_xor_b32_e32 v18, 16, v16
	v_cmp_lt_i32_e32 vcc, v18, v17
	s_mov_b32 s3, 0xe800000
	s_mov_b32 s8, 0xea00000
	v_cndmask_b32_e32 v18, v16, v18, vcc
	v_lshlrev_b32_e32 v28, 2, v18
	v_xor_b32_e32 v18, 32, v16
	v_cmp_lt_i32_e32 vcc, v18, v17
	s_mov_b32 s9, 0xec00000
	s_mov_b32 s12, 0xf200000
	v_cndmask_b32_e32 v16, v16, v18, vcc
	v_add_u32_e32 v18, 0x4000, v50
	v_ashrrev_i32_e32 v19, 31, v18
	v_lshlrev_b32_e32 v29, 2, v16
	v_lshlrev_b64 v[16:17], 12, v[50:51]
	v_lshlrev_b64 v[18:19], 12, v[18:19]
	v_lshl_add_u64 v[16:17], s[94:95], 0, v[16:17]
	v_lshl_add_u64 v[18:19], s[10:11], 0, v[18:19]
	s_mov_b32 s10, 0xee00000
	s_mov_b32 s11, 0xf000000
	s_mov_b32 s13, 0xf400000
	s_mov_b32 s14, 0xf600000
	s_mov_b32 s15, 0xf800000
	s_mov_b32 s16, 0xfa00000
	v_mov_b32_e32 v30, 0x358637bd
	v_mov_b32_e32 v31, 0x260
	s_movk_i32 s17, 0x1ff
